# final output stores with nt cache policy
# speedup vs baseline: 1.0060x; 1.0023x over previous
.LBB0_1420:
	s_or_b64 exec, exec, s[0:1]
	global_store_dwordx4 v[152:153], v[24:27], off nt
	global_store_dwordx4 v[154:155], v[28:31], off nt
	s_mov_b64 s[0:1], 0x80
	v_mov_b32_e32 v24, v20
	v_mov_b32_e32 v25, v20
	v_lshl_add_u64 v[28:29], v[164:165], 0, s[0:1]
	v_pk_mul_f32 v[26:27], v[148:149], v[24:25]
	v_pk_mul_f32 v[30:31], v[150:151], v[20:21]
	v_pk_mul_f32 v[24:25], v[144:145], v[24:25]
	v_pk_mul_f32 v[20:21], v[146:147], v[20:21]
	s_movk_i32 s0, 0x8090
	s_waitcnt vmcnt(2)
	v_pk_mul_f32 v[148:149], v[10:11], v[26:27]
	v_pk_mul_f32 v[150:151], v[8:9], v[30:31]
	v_pk_mul_f32 v[24:25], v[6:7], v[24:25]
	v_pk_mul_f32 v[26:27], v[4:5], v[20:21]
	v_mov_b32_e32 v20, 0
	v_mov_b32_e32 v21, 0
	v_mov_b32_e32 v22, 0
	s_mov_b32 s1, -1
	v_mov_b32_dpp v20, v26 row_ror:8 row_mask:0xf bank_mask:0xf
	v_mov_b32_dpp v21, v27 row_ror:8 row_mask:0xf bank_mask:0xf
	v_mov_b32_dpp v22, v24 row_ror:8 row_mask:0xf bank_mask:0xf
	v_mov_b32_dpp v23, v25 row_ror:8 row_mask:0xf bank_mask:0xf
	v_lshl_add_u64 v[30:31], v[164:165], 0, s[0:1]
	v_mov_b32_e32 v24, v150
	v_mov_b32_e32 v25, v151
	v_mov_b32_e32 v26, v148
	v_mov_b32_e32 v27, v149
	s_and_saveexec_b64 s[0:1], s[2:3]
	s_cbranch_execz .LBB0_1422
	s_mov_b64 s[4:5], 0x8090
	v_lshl_add_u64 v[144:145], v[164:165], 0, s[4:5]
	v_mov_b64_e32 v[30:31], v[28:29]
	v_mov_b32_e32 v24, v20
	v_mov_b32_e32 v25, v21
	v_mov_b32_e32 v26, v22
	v_mov_b32_e32 v27, v23
	v_mov_b32_e32 v20, v150
	v_mov_b32_e32 v21, v151
	v_mov_b32_e32 v22, v148
	v_mov_b32_e32 v23, v149
	v_mov_b64_e32 v[28:29], v[144:145]
.LBB0_1422:
	s_or_b64 exec, exec, s[0:1]
	global_store_dwordx4 v[30:31], v[20:23], off nt
	global_store_dwordx4 v[28:29], v[24:27], off nt
	s_andn2_b64 vcc, exec, s[6:7]
	v_cndmask_b32_e64 v20, 0, 1, s[6:7]
	v_cmp_ne_u32_e64 s[4:5], 1, v20
	v_mov_b32_e32 v20, 0x7fc00000
	s_cbranch_vccnz .LBB0_1424
	v_mov_b32_e32 v20, 0x100
	v_lshl_add_u32 v20, v168, 2, v20
	ds_read_b32 v20, v20 offset:4160

.LBB0_1426:
	s_or_b64 exec, exec, s[0:1]
	global_store_dwordx4 v[136:137], v[24:27], off nt
	global_store_dwordx4 v[138:139], v[28:31], off nt
	s_mov_b64 s[0:1], 0x80
	v_mov_b32_e32 v24, v20
	v_mov_b32_e32 v25, v20
	v_lshl_add_u64 v[28:29], v[144:145], 0, s[0:1]
	v_pk_mul_f32 v[26:27], v[132:133], v[24:25]
	v_pk_mul_f32 v[132:133], v[134:135], v[20:21]
	v_pk_mul_f32 v[24:25], v[126:127], v[24:25]
	v_pk_mul_f32 v[20:21], v[130:131], v[20:21]
	s_movk_i32 s0, 0x8090
	v_pk_mul_f32 v[30:31], v[10:11], v[26:27]
	v_pk_mul_f32 v[132:133], v[8:9], v[132:133]
	v_pk_mul_f32 v[24:25], v[6:7], v[24:25]
	v_pk_mul_f32 v[26:27], v[4:5], v[20:21]
	v_mov_b32_e32 v20, 0
	v_mov_b32_e32 v21, 0
	v_mov_b32_e32 v22, 0
	s_mov_b32 s1, -1
	v_mov_b32_dpp v20, v26 row_ror:8 row_mask:0xf bank_mask:0xf
	v_mov_b32_dpp v21, v27 row_ror:8 row_mask:0xf bank_mask:0xf
	v_mov_b32_dpp v22, v24 row_ror:8 row_mask:0xf bank_mask:0xf
	v_mov_b32_dpp v23, v25 row_ror:8 row_mask:0xf bank_mask:0xf
	v_lshl_add_u64 v[126:127], v[144:145], 0, s[0:1]
	v_mov_b32_e32 v24, v132
	v_mov_b32_e32 v25, v133
	v_mov_b32_e32 v26, v30
	v_mov_b32_e32 v27, v31
	s_and_saveexec_b64 s[0:1], s[2:3]
	s_cbranch_execz .LBB0_1428
	s_mov_b64 s[6:7], 0x8090
	v_lshl_add_u64 v[130:131], v[144:145], 0, s[6:7]
	v_mov_b64_e32 v[126:127], v[28:29]
	v_mov_b32_e32 v24, v20
	v_mov_b32_e32 v25, v21
	v_mov_b32_e32 v26, v22
	v_mov_b32_e32 v27, v23
	v_mov_b32_e32 v20, v132
	v_mov_b32_e32 v21, v133
	v_mov_b32_e32 v22, v30
	v_mov_b32_e32 v23, v31
	v_mov_b64_e32 v[28:29], v[130:131]
.LBB0_1428:
	s_or_b64 exec, exec, s[0:1]
	global_store_dwordx4 v[126:127], v[20:23], off nt
	global_store_dwordx4 v[28:29], v[24:27], off nt
	s_and_b64 vcc, exec, s[4:5]
	v_mov_b32_e32 v20, 0x7fc00000
	s_cbranch_vccnz .LBB0_1430
	v_mov_b32_e32 v20, 0x100
	v_lshl_add_u32 v20, v168, 2, v20
	ds_read_b32 v20, v20 offset:4224

.LBB0_1432:
	s_or_b64 exec, exec, s[0:1]
	global_store_dwordx4 v[120:121], v[24:27], off nt
	global_store_dwordx4 v[122:123], v[28:31], off nt
	s_mov_b64 s[0:1], 0x80
	v_mov_b32_e32 v24, v20
	v_mov_b32_e32 v25, v20
	v_lshl_add_u64 v[28:29], v[126:127], 0, s[0:1]
	v_pk_mul_f32 v[26:27], v[116:117], v[24:25]
	v_pk_mul_f32 v[116:117], v[118:119], v[20:21]
	v_pk_mul_f32 v[24:25], v[112:113], v[24:25]
	v_pk_mul_f32 v[20:21], v[114:115], v[20:21]
	s_movk_i32 s0, 0x8090
	v_pk_mul_f32 v[30:31], v[10:11], v[26:27]
	v_pk_mul_f32 v[116:117], v[8:9], v[116:117]
	v_pk_mul_f32 v[24:25], v[6:7], v[24:25]
	v_pk_mul_f32 v[26:27], v[4:5], v[20:21]
	v_mov_b32_e32 v20, 0
	v_mov_b32_e32 v21, 0
	v_mov_b32_e32 v22, 0
	s_mov_b32 s1, -1
	v_mov_b32_dpp v20, v26 row_ror:8 row_mask:0xf bank_mask:0xf
	v_mov_b32_dpp v21, v27 row_ror:8 row_mask:0xf bank_mask:0xf
	v_mov_b32_dpp v22, v24 row_ror:8 row_mask:0xf bank_mask:0xf
	v_mov_b32_dpp v23, v25 row_ror:8 row_mask:0xf bank_mask:0xf
	v_lshl_add_u64 v[112:113], v[126:127], 0, s[0:1]
	v_mov_b32_e32 v24, v116
	v_mov_b32_e32 v25, v117
	v_mov_b32_e32 v26, v30
	v_mov_b32_e32 v27, v31
	s_and_saveexec_b64 s[0:1], s[2:3]
	s_cbranch_execz .LBB0_1434
	s_mov_b64 s[6:7], 0x8090
	v_lshl_add_u64 v[114:115], v[126:127], 0, s[6:7]
	v_mov_b64_e32 v[112:113], v[28:29]
	v_mov_b32_e32 v24, v20
	v_mov_b32_e32 v25, v21
	v_mov_b32_e32 v26, v22
	v_mov_b32_e32 v27, v23
	v_mov_b32_e32 v20, v116
	v_mov_b32_e32 v21, v117
	v_mov_b32_e32 v22, v30
	v_mov_b32_e32 v23, v31
	v_mov_b64_e32 v[28:29], v[114:115]
.LBB0_1434:
	s_or_b64 exec, exec, s[0:1]
	global_store_dwordx4 v[112:113], v[20:23], off nt
	global_store_dwordx4 v[28:29], v[24:27], off nt
	s_and_b64 vcc, exec, s[4:5]
	v_mov_b32_e32 v20, 0x7fc00000
	s_cbranch_vccnz .LBB0_1436
	v_mov_b32_e32 v20, 0x100
	v_lshl_add_u32 v20, v168, 2, v20
	ds_read_b32 v20, v20 offset:4288

.LBB0_1438:
	s_or_b64 exec, exec, s[0:1]
	global_store_dwordx4 v[104:105], v[24:27], off nt
	global_store_dwordx4 v[106:107], v[28:31], off nt
	s_mov_b64 s[0:1], 0x80
	v_mov_b32_e32 v24, v20
	v_mov_b32_e32 v25, v20
	v_lshl_add_u64 v[28:29], v[112:113], 0, s[0:1]
	v_pk_mul_f32 v[26:27], v[100:101], v[24:25]
	v_pk_mul_f32 v[100:101], v[102:103], v[20:21]
	v_pk_mul_f32 v[24:25], v[94:95], v[24:25]
	v_pk_mul_f32 v[20:21], v[98:99], v[20:21]
	s_movk_i32 s0, 0x8090
	v_pk_mul_f32 v[30:31], v[10:11], v[26:27]
	v_pk_mul_f32 v[100:101], v[8:9], v[100:101]
	v_pk_mul_f32 v[24:25], v[6:7], v[24:25]
	v_pk_mul_f32 v[26:27], v[4:5], v[20:21]
	v_mov_b32_e32 v20, 0
	v_mov_b32_e32 v21, 0
	v_mov_b32_e32 v22, 0
	s_mov_b32 s1, -1
	v_mov_b32_dpp v20, v26 row_ror:8 row_mask:0xf bank_mask:0xf
	v_mov_b32_dpp v21, v27 row_ror:8 row_mask:0xf bank_mask:0xf
	v_mov_b32_dpp v22, v24 row_ror:8 row_mask:0xf bank_mask:0xf
	v_mov_b32_dpp v23, v25 row_ror:8 row_mask:0xf bank_mask:0xf
	v_lshl_add_u64 v[94:95], v[112:113], 0, s[0:1]
	v_mov_b32_e32 v24, v100
	v_mov_b32_e32 v25, v101
	v_mov_b32_e32 v26, v30
	v_mov_b32_e32 v27, v31
	s_and_saveexec_b64 s[0:1], s[2:3]
	s_cbranch_execz .LBB0_1440
	s_mov_b64 s[6:7], 0x8090
	v_lshl_add_u64 v[98:99], v[112:113], 0, s[6:7]
	v_mov_b64_e32 v[94:95], v[28:29]
	v_mov_b32_e32 v24, v20
	v_mov_b32_e32 v25, v21
	v_mov_b32_e32 v26, v22
	v_mov_b32_e32 v27, v23
	v_mov_b32_e32 v20, v100
	v_mov_b32_e32 v21, v101
	v_mov_b32_e32 v22, v30
	v_mov_b32_e32 v23, v31
	v_mov_b64_e32 v[28:29], v[98:99]
.LBB0_1440:
	s_or_b64 exec, exec, s[0:1]
	global_store_dwordx4 v[94:95], v[20:23], off nt
	global_store_dwordx4 v[28:29], v[24:27], off nt
	s_and_b64 vcc, exec, s[4:5]
	v_mov_b32_e32 v20, 0x7fc00000
	s_cbranch_vccnz .LBB0_1442
	v_mov_b32_e32 v20, 0x100
	v_lshl_add_u32 v20, v168, 2, v20
	ds_read_b32 v20, v20 offset:4608

.LBB0_1444:
	s_or_b64 exec, exec, s[0:1]
	global_store_dwordx4 v[88:89], v[24:27], off nt
	global_store_dwordx4 v[90:91], v[28:31], off nt
	s_mov_b64 s[0:1], 0x80
	v_mov_b32_e32 v24, v20
	v_mov_b32_e32 v25, v20
	v_lshl_add_u64 v[28:29], v[94:95], 0, s[0:1]
	v_pk_mul_f32 v[26:27], v[84:85], v[24:25]
	v_pk_mul_f32 v[84:85], v[86:87], v[20:21]
	v_pk_mul_f32 v[24:25], v[80:81], v[24:25]
	v_pk_mul_f32 v[20:21], v[82:83], v[20:21]
	s_movk_i32 s0, 0x8090
	v_pk_mul_f32 v[30:31], v[10:11], v[26:27]
	v_pk_mul_f32 v[84:85], v[8:9], v[84:85]
	v_pk_mul_f32 v[24:25], v[6:7], v[24:25]
	v_pk_mul_f32 v[26:27], v[4:5], v[20:21]
	v_mov_b32_e32 v20, 0
	v_mov_b32_e32 v21, 0
	v_mov_b32_e32 v22, 0
	s_mov_b32 s1, -1
	v_mov_b32_dpp v20, v26 row_ror:8 row_mask:0xf bank_mask:0xf
	v_mov_b32_dpp v21, v27 row_ror:8 row_mask:0xf bank_mask:0xf
	v_mov_b32_dpp v22, v24 row_ror:8 row_mask:0xf bank_mask:0xf
	v_mov_b32_dpp v23, v25 row_ror:8 row_mask:0xf bank_mask:0xf
	v_lshl_add_u64 v[80:81], v[94:95], 0, s[0:1]
	v_mov_b32_e32 v24, v84
	v_mov_b32_e32 v25, v85
	v_mov_b32_e32 v26, v30
	v_mov_b32_e32 v27, v31
	s_and_saveexec_b64 s[0:1], s[2:3]
	s_cbranch_execz .LBB0_1446
	s_mov_b64 s[6:7], 0x8090
	v_lshl_add_u64 v[82:83], v[94:95], 0, s[6:7]
	v_mov_b64_e32 v[80:81], v[28:29]
	v_mov_b32_e32 v24, v20
	v_mov_b32_e32 v25, v21
	v_mov_b32_e32 v26, v22
	v_mov_b32_e32 v27, v23
	v_mov_b32_e32 v20, v84
	v_mov_b32_e32 v21, v85
	v_mov_b32_e32 v22, v30
	v_mov_b32_e32 v23, v31
	v_mov_b64_e32 v[28:29], v[82:83]
.LBB0_1446:
	s_or_b64 exec, exec, s[0:1]
	global_store_dwordx4 v[80:81], v[20:23], off nt
	global_store_dwordx4 v[28:29], v[24:27], off nt
	s_and_b64 vcc, exec, s[4:5]
	v_mov_b32_e32 v20, 0x7fc00000
	s_cbranch_vccnz .LBB0_1448
	v_mov_b32_e32 v3, 0x100
	v_lshl_add_u32 v3, v168, 2, v3
	ds_read_b32 v20, v3 offset:4672

.LBB0_1450:
	s_or_b64 exec, exec, s[0:1]
	global_store_dwordx4 v[72:73], v[24:27], off nt
	global_store_dwordx4 v[74:75], v[28:31], off nt
	s_mov_b64 s[0:1], 0x80
	v_mov_b32_e32 v24, v20
	v_mov_b32_e32 v25, v20
	v_lshl_add_u64 v[28:29], v[80:81], 0, s[0:1]
	v_pk_mul_f32 v[26:27], v[68:69], v[24:25]
	v_pk_mul_f32 v[68:69], v[70:71], v[20:21]
	v_pk_mul_f32 v[24:25], v[62:63], v[24:25]
	v_pk_mul_f32 v[20:21], v[66:67], v[20:21]
	s_movk_i32 s0, 0x8090
	v_pk_mul_f32 v[30:31], v[10:11], v[26:27]
	v_pk_mul_f32 v[68:69], v[8:9], v[68:69]
	v_pk_mul_f32 v[24:25], v[6:7], v[24:25]
	v_pk_mul_f32 v[26:27], v[4:5], v[20:21]
	v_mov_b32_e32 v20, 0
	v_mov_b32_e32 v21, 0
	v_mov_b32_e32 v22, 0
	s_mov_b32 s1, -1
	v_mov_b32_dpp v20, v26 row_ror:8 row_mask:0xf bank_mask:0xf
	v_mov_b32_dpp v21, v27 row_ror:8 row_mask:0xf bank_mask:0xf
	v_mov_b32_dpp v22, v24 row_ror:8 row_mask:0xf bank_mask:0xf
	v_mov_b32_dpp v23, v25 row_ror:8 row_mask:0xf bank_mask:0xf
	v_lshl_add_u64 v[62:63], v[80:81], 0, s[0:1]
	v_mov_b32_e32 v24, v68
	v_mov_b32_e32 v25, v69
	v_mov_b32_e32 v26, v30
	v_mov_b32_e32 v27, v31
	s_and_saveexec_b64 s[0:1], s[2:3]
	s_cbranch_execz .LBB0_1452
	s_mov_b64 s[6:7], 0x8090
	v_lshl_add_u64 v[66:67], v[80:81], 0, s[6:7]
	v_mov_b64_e32 v[62:63], v[28:29]
	v_mov_b32_e32 v24, v20
	v_mov_b32_e32 v25, v21
	v_mov_b32_e32 v26, v22
	v_mov_b32_e32 v27, v23
	v_mov_b32_e32 v20, v68
	v_mov_b32_e32 v21, v69
	v_mov_b32_e32 v22, v30
	v_mov_b32_e32 v23, v31
	v_mov_b64_e32 v[28:29], v[66:67]
.LBB0_1452:
	s_or_b64 exec, exec, s[0:1]
	global_store_dwordx4 v[62:63], v[20:23], off nt
	global_store_dwordx4 v[28:29], v[24:27], off nt
	s_and_b64 vcc, exec, s[4:5]
	v_mov_b32_e32 v20, 0x7fc00000
	s_cbranch_vccnz .LBB0_1454
	v_mov_b32_e32 v3, 0x100
	v_lshl_add_u32 v3, v168, 2, v3
	ds_read_b32 v20, v3 offset:4736

.LBB0_1456:
	s_or_b64 exec, exec, s[0:1]
	global_store_dwordx4 v[56:57], v[24:27], off nt
	global_store_dwordx4 v[58:59], v[28:31], off nt
	s_mov_b64 s[0:1], 0x80
	v_mov_b32_e32 v24, v20
	v_mov_b32_e32 v25, v20
	v_lshl_add_u64 v[28:29], v[62:63], 0, s[0:1]
	v_pk_mul_f32 v[26:27], v[52:53], v[24:25]
	v_pk_mul_f32 v[52:53], v[54:55], v[20:21]
	v_pk_mul_f32 v[24:25], v[48:49], v[24:25]
	v_pk_mul_f32 v[20:21], v[50:51], v[20:21]
	s_movk_i32 s0, 0x8090
	v_pk_mul_f32 v[30:31], v[10:11], v[26:27]
	v_pk_mul_f32 v[52:53], v[8:9], v[52:53]
	v_pk_mul_f32 v[24:25], v[6:7], v[24:25]
	v_pk_mul_f32 v[26:27], v[4:5], v[20:21]
	v_mov_b32_e32 v20, 0
	v_mov_b32_e32 v21, 0
	v_mov_b32_e32 v22, 0
	s_mov_b32 s1, -1
	v_mov_b32_dpp v20, v26 row_ror:8 row_mask:0xf bank_mask:0xf
	v_mov_b32_dpp v21, v27 row_ror:8 row_mask:0xf bank_mask:0xf
	v_mov_b32_dpp v22, v24 row_ror:8 row_mask:0xf bank_mask:0xf
	v_mov_b32_dpp v23, v25 row_ror:8 row_mask:0xf bank_mask:0xf
	v_lshl_add_u64 v[48:49], v[62:63], 0, s[0:1]
	v_mov_b32_e32 v24, v52
	v_mov_b32_e32 v25, v53
	v_mov_b32_e32 v26, v30
	v_mov_b32_e32 v27, v31
	s_and_saveexec_b64 s[0:1], s[2:3]
	s_cbranch_execz .LBB0_1458
	s_mov_b64 s[6:7], 0x8090
	v_lshl_add_u64 v[50:51], v[62:63], 0, s[6:7]
	v_mov_b64_e32 v[48:49], v[28:29]
	v_mov_b32_e32 v24, v20
	v_mov_b32_e32 v25, v21
	v_mov_b32_e32 v26, v22
	v_mov_b32_e32 v27, v23
	v_mov_b32_e32 v20, v52
	v_mov_b32_e32 v21, v53
	v_mov_b32_e32 v22, v30
	v_mov_b32_e32 v23, v31
	v_mov_b64_e32 v[28:29], v[50:51]
.LBB0_1458:
	s_or_b64 exec, exec, s[0:1]
	global_store_dwordx4 v[48:49], v[20:23], off nt
	global_store_dwordx4 v[28:29], v[24:27], off nt
	s_and_b64 vcc, exec, s[4:5]
	v_mov_b32_e32 v22, 0x7fc00000
	s_cbranch_vccnz .LBB0_1460
	v_mov_b32_e32 v3, 0x100
	v_lshl_add_u32 v3, v168, 2, v3
	ds_read_b32 v22, v3 offset:4800

.LBB0_1462:
	s_or_b64 exec, exec, s[0:1]
	global_store_dwordx4 v[28:29], v[14:17], off nt
	global_store_dwordx4 v[30:31], v[18:21], off nt
	s_mov_b64 s[0:1], 0x80
	v_lshl_add_u64 v[14:15], v[0:1], 0, s[0:1]
	v_mov_b32_e32 v20, v22
	v_mov_b32_e32 v21, v22
	v_pk_mul_f32 v[16:17], v[36:37], v[20:21]
	v_pk_mul_f32 v[18:19], v[38:39], v[22:23]
	v_pk_mul_f32 v[16:17], v[10:11], v[16:17]
	v_pk_mul_f32 v[18:19], v[8:9], v[18:19]
	v_pk_mul_f32 v[8:9], v[32:33], v[20:21]
	v_pk_mul_f32 v[10:11], v[34:35], v[22:23]
	s_movk_i32 s0, 0x8090
	v_pk_mul_f32 v[6:7], v[6:7], v[8:9]
	v_pk_mul_f32 v[4:5], v[4:5], v[10:11]
	v_mov_b32_e32 v10, 0
	v_mov_b32_e32 v11, 0
	v_mov_b32_e32 v12, 0
	s_mov_b32 s1, -1
	v_mov_b32_dpp v10, v4 row_ror:8 row_mask:0xf bank_mask:0xf
	v_mov_b32_dpp v11, v5 row_ror:8 row_mask:0xf bank_mask:0xf
	v_mov_b32_dpp v12, v6 row_ror:8 row_mask:0xf bank_mask:0xf
	v_mov_b32_dpp v13, v7 row_ror:8 row_mask:0xf bank_mask:0xf
	v_lshl_add_u64 v[8:9], v[0:1], 0, s[0:1]
	v_mov_b32_e32 v4, v18
	v_mov_b32_e32 v5, v19
	v_mov_b32_e32 v6, v16
	v_mov_b32_e32 v7, v17
	s_and_saveexec_b64 s[0:1], s[2:3]
	s_cbranch_execz .LBB0_1464
	s_mov_b64 s[2:3], 0x8090
	v_lshl_add_u64 v[0:1], v[0:1], 0, s[2:3]
	v_mov_b64_e32 v[8:9], v[14:15]
	v_mov_b32_e32 v4, v10
	v_mov_b32_e32 v5, v11
	v_mov_b32_e32 v6, v12
	v_mov_b32_e32 v7, v13
	v_mov_b32_e32 v10, v18
	v_mov_b32_e32 v11, v19
	v_mov_b32_e32 v12, v16
	v_mov_b32_e32 v13, v17
	v_mov_b64_e32 v[14:15], v[0:1]
.LBB0_1464:
	s_or_b64 exec, exec, s[0:1]
	global_store_dwordx4 v[8:9], v[10:13], off nt
	global_store_dwordx4 v[14:15], v[4:7], off nt

.LBB0_1471:
	v_add_u32_e32 v6, 0x200, v6
	v_cmp_lt_u32_e32 vcc, s4, v6
	global_store_dwordx4 v[0:1], v[2:5], off nt
	s_or_b64 s[0:1], vcc, s[0:1]
	v_lshl_add_u64 v[0:1], v[0:1], 0, s[2:3]
	s_andn2_b64 exec, exec, s[0:1]
	s_cbranch_execnz .LBB0_1471
